# rw_lora and post1 g-LoRA: weight-operand addresses and the first two weight fetches issued at the top of the preceding input stage
# baseline (speedup 1.0000x reference)
.LBB0_944:
	s_lshl_b32 s18, s48, 4
	s_mov_b32 s10, 0xffffde00
	s_mov_b32 s11, -1
	s_mov_b32 s20, 0x2200
	s_mov_b32 s21, 0
	v_and_b32_e32 v112, 63, v164
	v_lshrrev_b32_e32 v113, 6, v164
	v_lshlrev_b32_e32 v107, 2, v112
	v_lshrrev_b32_e32 v114, 4, v112
	v_and_b32_e32 v115, 15, v112
	v_lshlrev_b32_e32 v111, 11, v114
	v_lshl_add_u32 v111, v113, 8, v111
	v_lshl_add_u32 v111, v115, 4, v111
	v_mul_u32_u24_e32 v110, 0x3000, v113
	v_add_u32_e32 v110, 0x2000, v110
	v_lshl_add_u32 v109, v114, 10, v110
	v_lshl_add_u32 v109, v115, 4, v109
	v_lshl_add_u32 v110, v112, 2, v110
	v_readlane_b32 s50, v255, 27
	v_readlane_b32 s51, v255, 28
	v_readlane_b32 s54, v255, 31
	v_readlane_b32 s55, v255, 32
	s_add_u32 s52, s50, 0x20000
	s_addc_u32 s53, s51, 0
	v_mov_b32_e32 v108, v111
	global_load_dwordx4 v[92:95], v108, s[50:51]
	v_add_u32_e32 v108, 0x2000, v108
	global_load_dwordx4 v[96:99], v108, s[50:51]
	v_add_u32_e32 v108, 0x2000, v108
	global_load_dword v50, v[2:3], off
	global_load_dword v51, v[4:5], off
	global_load_dword v52, v[6:7], off
	global_load_dword v53, v[8:9], off
	v_or_b32_e32 v20, s18, v220
	v_mad_i64_i32 v[22:23], s[0:1], v20, s23, v[14:15]
	v_lshl_add_u64 v[22:23], v[22:23], 0, s[16:17]
	v_lshl_add_u64 v[26:27], v[22:23], 0, v[0:1]
	v_lshl_add_u64 v[34:35], v[26:27], 0, s[10:11]
	v_lshl_add_u64 v[36:37], v[26:27], 0, s[20:21]
	global_load_ushort v38, v[26:27], off
	global_load_ushort v42, v[34:35], off
	global_load_ushort v46, v[36:37], off
	v_lshl_add_u64 v[28:29], v[22:23], 0, v[18:19]
	v_lshl_add_u64 v[34:35], v[28:29], 0, s[10:11]
	v_lshl_add_u64 v[36:37], v[28:29], 0, s[20:21]
	global_load_ushort v39, v[28:29], off
	global_load_ushort v43, v[34:35], off
	global_load_ushort v47, v[36:37], off
	v_or_b32_e32 v21, s18, v69
	v_mad_i64_i32 v[24:25], s[0:1], v21, s23, v[14:15]
	v_lshl_add_u64 v[24:25], v[24:25], 0, s[16:17]
	v_lshl_add_u64 v[30:31], v[24:25], 0, v[0:1]
	v_lshl_add_u64 v[34:35], v[30:31], 0, s[10:11]
	v_lshl_add_u64 v[36:37], v[30:31], 0, s[20:21]
	global_load_ushort v40, v[30:31], off
	global_load_ushort v44, v[34:35], off
	global_load_ushort v48, v[36:37], off
	v_lshl_add_u64 v[32:33], v[24:25], 0, v[18:19]
	v_lshl_add_u64 v[34:35], v[32:33], 0, s[10:11]
	v_lshl_add_u64 v[36:37], v[32:33], 0, s[20:21]
	global_load_ushort v41, v[32:33], off
	global_load_ushort v45, v[34:35], off
	global_load_ushort v49, v[36:37], off
	s_waitcnt vmcnt(0)
	v_and_b32_e32 v54, v71, v20
	v_lshlrev_b32_e32 v55, 16, v38
	v_lshlrev_b32_e32 v56, 16, v42
	v_lshlrev_b32_e32 v57, 16, v46
	v_cmp_ne_u32_e32 vcc, 0, v54
	s_nop 1
	v_cndmask_b32_e32 v56, 0, v56, vcc
	v_cmp_ne_u32_e32 vcc, s22, v54
	s_nop 1
	v_cndmask_b32_e32 v57, 0, v57, vcc
	v_sub_f32_e32 v56, v56, v55
	v_sub_f32_e32 v57, v57, v55
	v_mul_f32_e32 v56, v56, v50
	v_mul_f32_e32 v57, v57, v51
	v_add_f32_e32 v56, v56, v55
	v_add_f32_e32 v56, v56, v57
	v_add_f32_e64 v57, |v56|, |v56|
	v_mul_f32_e32 v58, 0x3fb8aa3b, v57
	v_rndne_f32_e32 v59, v58
	v_sub_f32_e32 v60, v58, v59
	v_fma_f32 v58, v57, s35, -v58
	v_fmac_f32_e32 v58, 0x32a5705f, v57
	v_add_f32_e32 v58, v60, v58
	v_cvt_i32_f32_e32 v59, v59
	v_exp_f32_e32 v58, v58
	v_cmp_ngt_f32_e32 vcc, s44, v57
	v_ldexp_f32 v58, v58, v59
	s_nop 0
	v_cndmask_b32_e32 v58, 0, v58, vcc
	v_cmp_nlt_f32_e32 vcc, s45, v57
	s_nop 1
	v_cndmask_b32_e32 v57, v73, v58, vcc
	v_add_f32_e32 v57, 1.0, v57
	v_rcp_f32_e32 v57, v57
	s_nop 0
	v_fma_f32 v58, v57, -2.0, 1.0
	v_mul_f32_e32 v57, v56, v56
	v_fmamk_f32 v59, v57, 0xbbbac73d, v72
	v_fmaak_f32 v59, v57, v59, 0xbd5c1c4e
	v_fmaak_f32 v59, v57, v59, 0x3e088382
	v_fmaak_f32 v59, v57, v59, 0xbeaaaa99
	v_mul_f32_e64 v59, |v56|, v59
	v_fma_f32 v59, v57, v59, |v56|
	v_cmp_nlt_f32_e64 vcc, |v56|, s34
	s_nop 1
	v_cndmask_b32_e32 v58, v59, v58, vcc
	v_bfi_b32 v56, s46, v58, v56
	ds_write_b32 v68, v56
	v_and_b32_e32 v54, v71, v20
	v_lshlrev_b32_e32 v55, 16, v39
	v_lshlrev_b32_e32 v56, 16, v43
	v_lshlrev_b32_e32 v57, 16, v47
	v_cmp_ne_u32_e32 vcc, 0, v54
	s_nop 1
	v_cndmask_b32_e32 v56, 0, v56, vcc
	v_cmp_ne_u32_e32 vcc, s22, v54
	s_nop 1
	v_cndmask_b32_e32 v57, 0, v57, vcc
	v_sub_f32_e32 v56, v56, v55
	v_sub_f32_e32 v57, v57, v55
	v_mul_f32_e32 v56, v56, v52
	v_mul_f32_e32 v57, v57, v53
	v_add_f32_e32 v56, v56, v55
	v_add_f32_e32 v56, v56, v57
	ds_write_b32 v68, v56 offset:4096
	v_and_b32_e32 v54, v71, v21
	v_lshlrev_b32_e32 v55, 16, v40
	v_lshlrev_b32_e32 v56, 16, v44
	v_lshlrev_b32_e32 v57, 16, v48
	v_cmp_ne_u32_e32 vcc, 0, v54
	s_nop 1
	v_cndmask_b32_e32 v56, 0, v56, vcc
	v_cmp_ne_u32_e32 vcc, s22, v54
	s_nop 1
	v_cndmask_b32_e32 v57, 0, v57, vcc
	v_sub_f32_e32 v56, v56, v55
	v_sub_f32_e32 v57, v57, v55
	v_mul_f32_e32 v56, v56, v50
	v_mul_f32_e32 v57, v57, v51
	v_add_f32_e32 v56, v56, v55
	v_add_f32_e32 v56, v56, v57
	v_add_f32_e64 v57, |v56|, |v56|
	v_mul_f32_e32 v58, 0x3fb8aa3b, v57
	v_rndne_f32_e32 v59, v58
	v_sub_f32_e32 v60, v58, v59
	v_fma_f32 v58, v57, s35, -v58
	v_fmac_f32_e32 v58, 0x32a5705f, v57
	v_add_f32_e32 v58, v60, v58
	v_cvt_i32_f32_e32 v59, v59
	v_exp_f32_e32 v58, v58
	v_cmp_ngt_f32_e32 vcc, s44, v57
	v_ldexp_f32 v58, v58, v59
	s_nop 0
	v_cndmask_b32_e32 v58, 0, v58, vcc
	v_cmp_nlt_f32_e32 vcc, s45, v57
	s_nop 1
	v_cndmask_b32_e32 v57, v73, v58, vcc
	v_add_f32_e32 v57, 1.0, v57
	v_rcp_f32_e32 v57, v57
	s_nop 0
	v_fma_f32 v58, v57, -2.0, 1.0
	v_mul_f32_e32 v57, v56, v56
	v_fmamk_f32 v59, v57, 0xbbbac73d, v72
	v_fmaak_f32 v59, v57, v59, 0xbd5c1c4e
	v_fmaak_f32 v59, v57, v59, 0x3e088382
	v_fmaak_f32 v59, v57, v59, 0xbeaaaa99
	v_mul_f32_e64 v59, |v56|, v59
	v_fma_f32 v59, v57, v59, |v56|
	v_cmp_nlt_f32_e64 vcc, |v56|, s34
	s_nop 1
	v_cndmask_b32_e32 v58, v59, v58, vcc
	v_bfi_b32 v56, s46, v58, v56
	ds_write_b32 v70, v56
	v_and_b32_e32 v54, v71, v21
	v_lshlrev_b32_e32 v55, 16, v41
	v_lshlrev_b32_e32 v56, 16, v45
	v_lshlrev_b32_e32 v57, 16, v49
	v_cmp_ne_u32_e32 vcc, 0, v54
	s_nop 1
	v_cndmask_b32_e32 v56, 0, v56, vcc
	v_cmp_ne_u32_e32 vcc, s22, v54
	s_nop 1
	v_cndmask_b32_e32 v57, 0, v57, vcc
	v_sub_f32_e32 v56, v56, v55
	v_sub_f32_e32 v57, v57, v55
	v_mul_f32_e32 v56, v56, v52
	v_mul_f32_e32 v57, v57, v53
	v_add_f32_e32 v56, v56, v55
	v_add_f32_e32 v56, v56, v57
	ds_write_b32 v70, v56 offset:4096
	s_waitcnt lgkmcnt(0)
	s_barrier
	ds_read_b32 v104, v107 offset:0
	ds_read_b32 v105, v107 offset:256
	global_load_dwordx4 v[100:103], v108, s[50:51]
	v_add_u32_e32 v108, 0x2000, v108
	ds_read_b32 v106, v107 offset:512
	s_waitcnt vmcnt(2) lgkmcnt(2)
	v_mfma_f32_16x16x4_f32 v[76:79], v104, v92, 0
	v_mfma_f32_16x16x4_f32 v[80:83], v104, v93, 0
	v_mfma_f32_16x16x4_f32 v[84:87], v104, v94, 0
	v_mfma_f32_16x16x4_f32 v[88:91], v104, v95, 0
	global_load_dwordx4 v[92:95], v108, s[50:51]
	v_add_u32_e32 v108, 0x2000, v108
	ds_read_b32 v104, v107 offset:768
	s_waitcnt vmcnt(2) lgkmcnt(2)
	v_mfma_f32_16x16x4_f32 v[76:79], v105, v96, v[76:79]
	v_mfma_f32_16x16x4_f32 v[80:83], v105, v97, v[80:83]
	v_mfma_f32_16x16x4_f32 v[84:87], v105, v98, v[84:87]
	v_mfma_f32_16x16x4_f32 v[88:91], v105, v99, v[88:91]
	global_load_dwordx4 v[96:99], v108, s[50:51]
	v_add_u32_e32 v108, 0x2000, v108
	ds_read_b32 v105, v107 offset:1024
	s_waitcnt vmcnt(2) lgkmcnt(2)
	v_mfma_f32_16x16x4_f32 v[76:79], v106, v100, v[76:79]
	v_mfma_f32_16x16x4_f32 v[80:83], v106, v101, v[80:83]
	v_mfma_f32_16x16x4_f32 v[84:87], v106, v102, v[84:87]
	v_mfma_f32_16x16x4_f32 v[88:91], v106, v103, v[88:91]
	global_load_dwordx4 v[100:103], v108, s[50:51]
	v_add_u32_e32 v108, 0x2000, v108
	ds_read_b32 v106, v107 offset:1280
	s_waitcnt vmcnt(2) lgkmcnt(2)
	v_mfma_f32_16x16x4_f32 v[76:79], v104, v92, v[76:79]
	v_mfma_f32_16x16x4_f32 v[80:83], v104, v93, v[80:83]
	v_mfma_f32_16x16x4_f32 v[84:87], v104, v94, v[84:87]
	v_mfma_f32_16x16x4_f32 v[88:91], v104, v95, v[88:91]
	global_load_dwordx4 v[92:95], v108, s[50:51]
	v_add_u32_e32 v108, 0x2000, v108
	ds_read_b32 v104, v107 offset:1536
	s_waitcnt vmcnt(2) lgkmcnt(2)
	v_mfma_f32_16x16x4_f32 v[76:79], v105, v96, v[76:79]
	v_mfma_f32_16x16x4_f32 v[80:83], v105, v97, v[80:83]
	v_mfma_f32_16x16x4_f32 v[84:87], v105, v98, v[84:87]
	v_mfma_f32_16x16x4_f32 v[88:91], v105, v99, v[88:91]
	global_load_dwordx4 v[96:99], v108, s[50:51]
	v_add_u32_e32 v108, 0x2000, v108
	ds_read_b32 v105, v107 offset:1792
	s_waitcnt vmcnt(2) lgkmcnt(2)
	v_mfma_f32_16x16x4_f32 v[76:79], v106, v100, v[76:79]
	v_mfma_f32_16x16x4_f32 v[80:83], v106, v101, v[80:83]
	v_mfma_f32_16x16x4_f32 v[84:87], v106, v102, v[84:87]
	v_mfma_f32_16x16x4_f32 v[88:91], v106, v103, v[88:91]
	global_load_dwordx4 v[100:103], v108, s[50:51]
	v_add_u32_e32 v108, 0x2000, v108
	ds_read_b32 v106, v107 offset:2048
	s_waitcnt vmcnt(2) lgkmcnt(2)
	v_mfma_f32_16x16x4_f32 v[76:79], v104, v92, v[76:79]
	v_mfma_f32_16x16x4_f32 v[80:83], v104, v93, v[80:83]
	v_mfma_f32_16x16x4_f32 v[84:87], v104, v94, v[84:87]
	v_mfma_f32_16x16x4_f32 v[88:91], v104, v95, v[88:91]
	global_load_dwordx4 v[92:95], v108, s[50:51]
	v_add_u32_e32 v108, 0x2000, v108
	ds_read_b32 v104, v107 offset:2304
	s_waitcnt vmcnt(2) lgkmcnt(2)
	v_mfma_f32_16x16x4_f32 v[76:79], v105, v96, v[76:79]
	v_mfma_f32_16x16x4_f32 v[80:83], v105, v97, v[80:83]
	v_mfma_f32_16x16x4_f32 v[84:87], v105, v98, v[84:87]
	v_mfma_f32_16x16x4_f32 v[88:91], v105, v99, v[88:91]
	global_load_dwordx4 v[96:99], v108, s[50:51]
	v_add_u32_e32 v108, 0x2000, v108
	ds_read_b32 v105, v107 offset:2560
	s_waitcnt vmcnt(2) lgkmcnt(2)
	v_mfma_f32_16x16x4_f32 v[76:79], v106, v100, v[76:79]
	v_mfma_f32_16x16x4_f32 v[80:83], v106, v101, v[80:83]
	v_mfma_f32_16x16x4_f32 v[84:87], v106, v102, v[84:87]
	v_mfma_f32_16x16x4_f32 v[88:91], v106, v103, v[88:91]
	global_load_dwordx4 v[100:103], v108, s[50:51]
	v_add_u32_e32 v108, 0x2000, v108
	ds_read_b32 v106, v107 offset:2816
	s_waitcnt vmcnt(2) lgkmcnt(2)
	v_mfma_f32_16x16x4_f32 v[76:79], v104, v92, v[76:79]
	v_mfma_f32_16x16x4_f32 v[80:83], v104, v93, v[80:83]
	v_mfma_f32_16x16x4_f32 v[84:87], v104, v94, v[84:87]
	v_mfma_f32_16x16x4_f32 v[88:91], v104, v95, v[88:91]
	global_load_dwordx4 v[92:95], v108, s[50:51]
	v_add_u32_e32 v108, 0x2000, v108
	ds_read_b32 v104, v107 offset:3072
	s_waitcnt vmcnt(2) lgkmcnt(2)
	v_mfma_f32_16x16x4_f32 v[76:79], v105, v96, v[76:79]
	v_mfma_f32_16x16x4_f32 v[80:83], v105, v97, v[80:83]
	v_mfma_f32_16x16x4_f32 v[84:87], v105, v98, v[84:87]
	v_mfma_f32_16x16x4_f32 v[88:91], v105, v99, v[88:91]
	global_load_dwordx4 v[96:99], v108, s[50:51]
	v_add_u32_e32 v108, 0x2000, v108
	ds_read_b32 v105, v107 offset:3328
	s_waitcnt vmcnt(2) lgkmcnt(2)
	v_mfma_f32_16x16x4_f32 v[76:79], v106, v100, v[76:79]
	v_mfma_f32_16x16x4_f32 v[80:83], v106, v101, v[80:83]
	v_mfma_f32_16x16x4_f32 v[84:87], v106, v102, v[84:87]
	v_mfma_f32_16x16x4_f32 v[88:91], v106, v103, v[88:91]
	global_load_dwordx4 v[100:103], v108, s[50:51]
	v_add_u32_e32 v108, 0x2000, v108
	ds_read_b32 v106, v107 offset:3584
	s_waitcnt vmcnt(2) lgkmcnt(2)
	v_mfma_f32_16x16x4_f32 v[76:79], v104, v92, v[76:79]
	v_mfma_f32_16x16x4_f32 v[80:83], v104, v93, v[80:83]
	v_mfma_f32_16x16x4_f32 v[84:87], v104, v94, v[84:87]
	v_mfma_f32_16x16x4_f32 v[88:91], v104, v95, v[88:91]
	global_load_dwordx4 v[92:95], v108, s[50:51]
	v_add_u32_e32 v108, 0x2000, v108
	ds_read_b32 v104, v107 offset:3840
	s_waitcnt vmcnt(2) lgkmcnt(2)
	v_mfma_f32_16x16x4_f32 v[76:79], v105, v96, v[76:79]
	v_mfma_f32_16x16x4_f32 v[80:83], v105, v97, v[80:83]
	v_mfma_f32_16x16x4_f32 v[84:87], v105, v98, v[84:87]
	v_mfma_f32_16x16x4_f32 v[88:91], v105, v99, v[88:91]
	v_mov_b32_e32 v108, v111
	global_load_dwordx4 v[96:99], v108, s[52:53]
	v_add_u32_e32 v108, 0x2000, v108
	ds_read_b32 v105, v107 offset:0
	s_waitcnt vmcnt(2) lgkmcnt(2)
	v_mfma_f32_16x16x4_f32 v[76:79], v106, v100, v[76:79]
	v_mfma_f32_16x16x4_f32 v[80:83], v106, v101, v[80:83]
	v_mfma_f32_16x16x4_f32 v[84:87], v106, v102, v[84:87]
	v_mfma_f32_16x16x4_f32 v[88:91], v106, v103, v[88:91]
	global_load_dwordx4 v[100:103], v108, s[52:53]
	v_add_u32_e32 v108, 0x2000, v108
	ds_read_b32 v106, v107 offset:256
	s_waitcnt vmcnt(2) lgkmcnt(2)
	v_mfma_f32_16x16x4_f32 v[76:79], v104, v92, v[76:79]
	v_mfma_f32_16x16x4_f32 v[80:83], v104, v93, v[80:83]
	v_mfma_f32_16x16x4_f32 v[84:87], v104, v94, v[84:87]
	v_mfma_f32_16x16x4_f32 v[88:91], v104, v95, v[88:91]
	s_nop 7
	ds_write_b32 v109, v76 offset:0
	ds_write_b32 v109, v77 offset:256
	ds_write_b32 v109, v78 offset:512
	ds_write_b32 v109, v79 offset:768
	ds_write_b32 v109, v80 offset:4
	ds_write_b32 v109, v81 offset:260
	ds_write_b32 v109, v82 offset:516
	ds_write_b32 v109, v83 offset:772
	ds_write_b32 v109, v84 offset:8
	ds_write_b32 v109, v85 offset:264
	ds_write_b32 v109, v86 offset:520
	ds_write_b32 v109, v87 offset:776
	s_nop 15
	s_nop 3
	ds_write_b32 v109, v88 offset:12
	ds_write_b32 v109, v89 offset:268
	ds_write_b32 v109, v90 offset:524
	ds_write_b32 v109, v91 offset:780
	s_waitcnt lgkmcnt(0)
	global_load_dwordx4 v[92:95], v108, s[52:53]
	v_add_u32_e32 v108, 0x2000, v108
	ds_read_b32 v104, v107 offset:512
	s_waitcnt vmcnt(2) lgkmcnt(2)
	v_mfma_f32_16x16x4_f32 v[76:79], v105, v96, 0
	v_mfma_f32_16x16x4_f32 v[80:83], v105, v97, 0
	v_mfma_f32_16x16x4_f32 v[84:87], v105, v98, 0
	v_mfma_f32_16x16x4_f32 v[88:91], v105, v99, 0
	global_load_dwordx4 v[96:99], v108, s[52:53]
	v_add_u32_e32 v108, 0x2000, v108
	ds_read_b32 v105, v107 offset:768
	s_waitcnt vmcnt(2) lgkmcnt(2)
	v_mfma_f32_16x16x4_f32 v[76:79], v106, v100, v[76:79]
	v_mfma_f32_16x16x4_f32 v[80:83], v106, v101, v[80:83]
	v_mfma_f32_16x16x4_f32 v[84:87], v106, v102, v[84:87]
	v_mfma_f32_16x16x4_f32 v[88:91], v106, v103, v[88:91]
	global_load_dwordx4 v[100:103], v108, s[52:53]
	v_add_u32_e32 v108, 0x2000, v108
	ds_read_b32 v106, v107 offset:1024
	s_waitcnt vmcnt(2) lgkmcnt(2)
	v_mfma_f32_16x16x4_f32 v[76:79], v104, v92, v[76:79]
	v_mfma_f32_16x16x4_f32 v[80:83], v104, v93, v[80:83]
	v_mfma_f32_16x16x4_f32 v[84:87], v104, v94, v[84:87]
	v_mfma_f32_16x16x4_f32 v[88:91], v104, v95, v[88:91]
	global_load_dwordx4 v[92:95], v108, s[52:53]
	v_add_u32_e32 v108, 0x2000, v108
	ds_read_b32 v104, v107 offset:1280
	s_waitcnt vmcnt(2) lgkmcnt(2)
	v_mfma_f32_16x16x4_f32 v[76:79], v105, v96, v[76:79]
	v_mfma_f32_16x16x4_f32 v[80:83], v105, v97, v[80:83]
	v_mfma_f32_16x16x4_f32 v[84:87], v105, v98, v[84:87]
	v_mfma_f32_16x16x4_f32 v[88:91], v105, v99, v[88:91]
	global_load_dwordx4 v[96:99], v108, s[52:53]
	v_add_u32_e32 v108, 0x2000, v108
	ds_read_b32 v105, v107 offset:1536
	s_waitcnt vmcnt(2) lgkmcnt(2)
	v_mfma_f32_16x16x4_f32 v[76:79], v106, v100, v[76:79]
	v_mfma_f32_16x16x4_f32 v[80:83], v106, v101, v[80:83]
	v_mfma_f32_16x16x4_f32 v[84:87], v106, v102, v[84:87]
	v_mfma_f32_16x16x4_f32 v[88:91], v106, v103, v[88:91]
	global_load_dwordx4 v[100:103], v108, s[52:53]
	v_add_u32_e32 v108, 0x2000, v108
	ds_read_b32 v106, v107 offset:1792
	s_waitcnt vmcnt(2) lgkmcnt(2)
	v_mfma_f32_16x16x4_f32 v[76:79], v104, v92, v[76:79]
	v_mfma_f32_16x16x4_f32 v[80:83], v104, v93, v[80:83]
	v_mfma_f32_16x16x4_f32 v[84:87], v104, v94, v[84:87]
	v_mfma_f32_16x16x4_f32 v[88:91], v104, v95, v[88:91]
	global_load_dwordx4 v[92:95], v108, s[52:53]
	v_add_u32_e32 v108, 0x2000, v108
	ds_read_b32 v104, v107 offset:2048
	s_waitcnt vmcnt(2) lgkmcnt(2)
	v_mfma_f32_16x16x4_f32 v[76:79], v105, v96, v[76:79]
	v_mfma_f32_16x16x4_f32 v[80:83], v105, v97, v[80:83]
	v_mfma_f32_16x16x4_f32 v[84:87], v105, v98, v[84:87]
	v_mfma_f32_16x16x4_f32 v[88:91], v105, v99, v[88:91]
	global_load_dwordx4 v[96:99], v108, s[52:53]
	v_add_u32_e32 v108, 0x2000, v108
	ds_read_b32 v105, v107 offset:2304
	s_waitcnt vmcnt(2) lgkmcnt(2)
	v_mfma_f32_16x16x4_f32 v[76:79], v106, v100, v[76:79]
	v_mfma_f32_16x16x4_f32 v[80:83], v106, v101, v[80:83]
	v_mfma_f32_16x16x4_f32 v[84:87], v106, v102, v[84:87]
	v_mfma_f32_16x16x4_f32 v[88:91], v106, v103, v[88:91]
	global_load_dwordx4 v[100:103], v108, s[52:53]
	v_add_u32_e32 v108, 0x2000, v108
	ds_read_b32 v106, v107 offset:2560
	s_waitcnt vmcnt(2) lgkmcnt(2)
	v_mfma_f32_16x16x4_f32 v[76:79], v104, v92, v[76:79]
	v_mfma_f32_16x16x4_f32 v[80:83], v104, v93, v[80:83]
	v_mfma_f32_16x16x4_f32 v[84:87], v104, v94, v[84:87]
	v_mfma_f32_16x16x4_f32 v[88:91], v104, v95, v[88:91]
	global_load_dwordx4 v[92:95], v108, s[52:53]
	v_add_u32_e32 v108, 0x2000, v108
	ds_read_b32 v104, v107 offset:2816
	s_waitcnt vmcnt(2) lgkmcnt(2)
	v_mfma_f32_16x16x4_f32 v[76:79], v105, v96, v[76:79]
	v_mfma_f32_16x16x4_f32 v[80:83], v105, v97, v[80:83]
	v_mfma_f32_16x16x4_f32 v[84:87], v105, v98, v[84:87]
	v_mfma_f32_16x16x4_f32 v[88:91], v105, v99, v[88:91]
	global_load_dwordx4 v[96:99], v108, s[52:53]
	v_add_u32_e32 v108, 0x2000, v108
	ds_read_b32 v105, v107 offset:3072
	s_waitcnt vmcnt(2) lgkmcnt(2)
	v_mfma_f32_16x16x4_f32 v[76:79], v106, v100, v[76:79]
	v_mfma_f32_16x16x4_f32 v[80:83], v106, v101, v[80:83]
	v_mfma_f32_16x16x4_f32 v[84:87], v106, v102, v[84:87]
	v_mfma_f32_16x16x4_f32 v[88:91], v106, v103, v[88:91]
	global_load_dwordx4 v[100:103], v108, s[52:53]
	v_add_u32_e32 v108, 0x2000, v108
	ds_read_b32 v106, v107 offset:3328
	s_waitcnt vmcnt(2) lgkmcnt(2)
	v_mfma_f32_16x16x4_f32 v[76:79], v104, v92, v[76:79]
	v_mfma_f32_16x16x4_f32 v[80:83], v104, v93, v[80:83]
	v_mfma_f32_16x16x4_f32 v[84:87], v104, v94, v[84:87]
	v_mfma_f32_16x16x4_f32 v[88:91], v104, v95, v[88:91]
	global_load_dwordx4 v[92:95], v108, s[52:53]
	v_add_u32_e32 v108, 0x2000, v108
	ds_read_b32 v104, v107 offset:3584
	s_waitcnt vmcnt(2) lgkmcnt(2)
	v_mfma_f32_16x16x4_f32 v[76:79], v105, v96, v[76:79]
	v_mfma_f32_16x16x4_f32 v[80:83], v105, v97, v[80:83]
	v_mfma_f32_16x16x4_f32 v[84:87], v105, v98, v[84:87]
	v_mfma_f32_16x16x4_f32 v[88:91], v105, v99, v[88:91]
	global_load_dwordx4 v[96:99], v108, s[52:53]
	v_add_u32_e32 v108, 0x2000, v108
	ds_read_b32 v105, v107 offset:3840
	s_waitcnt vmcnt(2) lgkmcnt(2)
	v_mfma_f32_16x16x4_f32 v[76:79], v106, v100, v[76:79]
	v_mfma_f32_16x16x4_f32 v[80:83], v106, v101, v[80:83]
	v_mfma_f32_16x16x4_f32 v[84:87], v106, v102, v[84:87]
	v_mfma_f32_16x16x4_f32 v[88:91], v106, v103, v[88:91]
	v_mov_b32_e32 v108, v111
	global_load_dwordx4 v[100:103], v108, s[54:55]
	v_add_u32_e32 v108, 0x2000, v108
	ds_read_b32 v106, v107 offset:4096
	s_waitcnt vmcnt(2) lgkmcnt(2)
	v_mfma_f32_16x16x4_f32 v[76:79], v104, v92, v[76:79]
	v_mfma_f32_16x16x4_f32 v[80:83], v104, v93, v[80:83]
	v_mfma_f32_16x16x4_f32 v[84:87], v104, v94, v[84:87]
	v_mfma_f32_16x16x4_f32 v[88:91], v104, v95, v[88:91]
	global_load_dwordx4 v[92:95], v108, s[54:55]
	v_add_u32_e32 v108, 0x2000, v108
	ds_read_b32 v104, v107 offset:4352
	s_waitcnt vmcnt(2) lgkmcnt(2)
	v_mfma_f32_16x16x4_f32 v[76:79], v105, v96, v[76:79]
	v_mfma_f32_16x16x4_f32 v[80:83], v105, v97, v[80:83]
	v_mfma_f32_16x16x4_f32 v[84:87], v105, v98, v[84:87]
	v_mfma_f32_16x16x4_f32 v[88:91], v105, v99, v[88:91]
	s_nop 7
	ds_write_b32 v109, v76 offset:4096
	ds_write_b32 v109, v77 offset:4352
	ds_write_b32 v109, v78 offset:4608
	ds_write_b32 v109, v79 offset:4864
	ds_write_b32 v109, v80 offset:4100
	ds_write_b32 v109, v81 offset:4356
	ds_write_b32 v109, v82 offset:4612
	ds_write_b32 v109, v83 offset:4868
	ds_write_b32 v109, v84 offset:4104
	ds_write_b32 v109, v85 offset:4360
	ds_write_b32 v109, v86 offset:4616
	ds_write_b32 v109, v87 offset:4872
	s_nop 15
	s_nop 3
	ds_write_b32 v109, v88 offset:4108
	ds_write_b32 v109, v89 offset:4364
	ds_write_b32 v109, v90 offset:4620
	ds_write_b32 v109, v91 offset:4876
	s_waitcnt lgkmcnt(0)
	global_load_dwordx4 v[96:99], v108, s[54:55]
	v_add_u32_e32 v108, 0x2000, v108
	ds_read_b32 v105, v107 offset:4608
	s_waitcnt vmcnt(2) lgkmcnt(2)
	v_mfma_f32_16x16x4_f32 v[76:79], v106, v100, 0
	v_mfma_f32_16x16x4_f32 v[80:83], v106, v101, 0
	v_mfma_f32_16x16x4_f32 v[84:87], v106, v102, 0
	v_mfma_f32_16x16x4_f32 v[88:91], v106, v103, 0
	global_load_dwordx4 v[100:103], v108, s[54:55]
	v_add_u32_e32 v108, 0x2000, v108
	ds_read_b32 v106, v107 offset:4864
	s_waitcnt vmcnt(2) lgkmcnt(2)
	v_mfma_f32_16x16x4_f32 v[76:79], v104, v92, v[76:79]
	v_mfma_f32_16x16x4_f32 v[80:83], v104, v93, v[80:83]
	v_mfma_f32_16x16x4_f32 v[84:87], v104, v94, v[84:87]
	v_mfma_f32_16x16x4_f32 v[88:91], v104, v95, v[88:91]
	global_load_dwordx4 v[92:95], v108, s[54:55]
	v_add_u32_e32 v108, 0x2000, v108
	ds_read_b32 v104, v107 offset:5120
	s_waitcnt vmcnt(2) lgkmcnt(2)
	v_mfma_f32_16x16x4_f32 v[76:79], v105, v96, v[76:79]
	v_mfma_f32_16x16x4_f32 v[80:83], v105, v97, v[80:83]
	v_mfma_f32_16x16x4_f32 v[84:87], v105, v98, v[84:87]
	v_mfma_f32_16x16x4_f32 v[88:91], v105, v99, v[88:91]
	global_load_dwordx4 v[96:99], v108, s[54:55]
	v_add_u32_e32 v108, 0x2000, v108
	ds_read_b32 v105, v107 offset:5376
	s_waitcnt vmcnt(2) lgkmcnt(2)
	v_mfma_f32_16x16x4_f32 v[76:79], v106, v100, v[76:79]
	v_mfma_f32_16x16x4_f32 v[80:83], v106, v101, v[80:83]
	v_mfma_f32_16x16x4_f32 v[84:87], v106, v102, v[84:87]
	v_mfma_f32_16x16x4_f32 v[88:91], v106, v103, v[88:91]
	global_load_dwordx4 v[100:103], v108, s[54:55]
	v_add_u32_e32 v108, 0x2000, v108
	ds_read_b32 v106, v107 offset:5632
	s_waitcnt vmcnt(2) lgkmcnt(2)
	v_mfma_f32_16x16x4_f32 v[76:79], v104, v92, v[76:79]
	v_mfma_f32_16x16x4_f32 v[80:83], v104, v93, v[80:83]
	v_mfma_f32_16x16x4_f32 v[84:87], v104, v94, v[84:87]
	v_mfma_f32_16x16x4_f32 v[88:91], v104, v95, v[88:91]
	global_load_dwordx4 v[92:95], v108, s[54:55]
	v_add_u32_e32 v108, 0x2000, v108
	ds_read_b32 v104, v107 offset:5888
	s_waitcnt vmcnt(2) lgkmcnt(2)
	v_mfma_f32_16x16x4_f32 v[76:79], v105, v96, v[76:79]
	v_mfma_f32_16x16x4_f32 v[80:83], v105, v97, v[80:83]
	v_mfma_f32_16x16x4_f32 v[84:87], v105, v98, v[84:87]
	v_mfma_f32_16x16x4_f32 v[88:91], v105, v99, v[88:91]
	global_load_dwordx4 v[96:99], v108, s[54:55]
	v_add_u32_e32 v108, 0x2000, v108
	ds_read_b32 v105, v107 offset:6144
	s_waitcnt vmcnt(2) lgkmcnt(2)
	v_mfma_f32_16x16x4_f32 v[76:79], v106, v100, v[76:79]
	v_mfma_f32_16x16x4_f32 v[80:83], v106, v101, v[80:83]
	v_mfma_f32_16x16x4_f32 v[84:87], v106, v102, v[84:87]
	v_mfma_f32_16x16x4_f32 v[88:91], v106, v103, v[88:91]
	global_load_dwordx4 v[100:103], v108, s[54:55]
	v_add_u32_e32 v108, 0x2000, v108
	ds_read_b32 v106, v107 offset:6400
	s_waitcnt vmcnt(2) lgkmcnt(2)
	v_mfma_f32_16x16x4_f32 v[76:79], v104, v92, v[76:79]
	v_mfma_f32_16x16x4_f32 v[80:83], v104, v93, v[80:83]
	v_mfma_f32_16x16x4_f32 v[84:87], v104, v94, v[84:87]
	v_mfma_f32_16x16x4_f32 v[88:91], v104, v95, v[88:91]
	global_load_dwordx4 v[92:95], v108, s[54:55]
	v_add_u32_e32 v108, 0x2000, v108
	ds_read_b32 v104, v107 offset:6656
	s_waitcnt vmcnt(2) lgkmcnt(2)
	v_mfma_f32_16x16x4_f32 v[76:79], v105, v96, v[76:79]
	v_mfma_f32_16x16x4_f32 v[80:83], v105, v97, v[80:83]
	v_mfma_f32_16x16x4_f32 v[84:87], v105, v98, v[84:87]
	v_mfma_f32_16x16x4_f32 v[88:91], v105, v99, v[88:91]
	global_load_dwordx4 v[96:99], v108, s[54:55]
	v_add_u32_e32 v108, 0x2000, v108
	ds_read_b32 v105, v107 offset:6912
	s_waitcnt vmcnt(2) lgkmcnt(2)
	v_mfma_f32_16x16x4_f32 v[76:79], v106, v100, v[76:79]
	v_mfma_f32_16x16x4_f32 v[80:83], v106, v101, v[80:83]
	v_mfma_f32_16x16x4_f32 v[84:87], v106, v102, v[84:87]
	v_mfma_f32_16x16x4_f32 v[88:91], v106, v103, v[88:91]
	global_load_dwordx4 v[100:103], v108, s[54:55]
	v_add_u32_e32 v108, 0x2000, v108
	ds_read_b32 v106, v107 offset:7168
	s_waitcnt vmcnt(2) lgkmcnt(2)
	v_mfma_f32_16x16x4_f32 v[76:79], v104, v92, v[76:79]
	v_mfma_f32_16x16x4_f32 v[80:83], v104, v93, v[80:83]
	v_mfma_f32_16x16x4_f32 v[84:87], v104, v94, v[84:87]
	v_mfma_f32_16x16x4_f32 v[88:91], v104, v95, v[88:91]
	global_load_dwordx4 v[92:95], v108, s[54:55]
	v_add_u32_e32 v108, 0x2000, v108
	ds_read_b32 v104, v107 offset:7424
	s_waitcnt vmcnt(2) lgkmcnt(2)
	v_mfma_f32_16x16x4_f32 v[76:79], v105, v96, v[76:79]
	v_mfma_f32_16x16x4_f32 v[80:83], v105, v97, v[80:83]
	v_mfma_f32_16x16x4_f32 v[84:87], v105, v98, v[84:87]
	v_mfma_f32_16x16x4_f32 v[88:91], v105, v99, v[88:91]
	global_load_dwordx4 v[96:99], v108, s[54:55]
	v_add_u32_e32 v108, 0x2000, v108
	ds_read_b32 v105, v107 offset:7680
	s_waitcnt vmcnt(2) lgkmcnt(2)
	v_mfma_f32_16x16x4_f32 v[76:79], v106, v100, v[76:79]
	v_mfma_f32_16x16x4_f32 v[80:83], v106, v101, v[80:83]
	v_mfma_f32_16x16x4_f32 v[84:87], v106, v102, v[84:87]
	v_mfma_f32_16x16x4_f32 v[88:91], v106, v103, v[88:91]
	global_load_dwordx4 v[100:103], v108, s[54:55]
	v_add_u32_e32 v108, 0x2000, v108
	ds_read_b32 v106, v107 offset:7936
	s_waitcnt vmcnt(2) lgkmcnt(2)
	v_mfma_f32_16x16x4_f32 v[76:79], v104, v92, v[76:79]
	v_mfma_f32_16x16x4_f32 v[80:83], v104, v93, v[80:83]
	v_mfma_f32_16x16x4_f32 v[84:87], v104, v94, v[84:87]
	v_mfma_f32_16x16x4_f32 v[88:91], v104, v95, v[88:91]
	s_waitcnt vmcnt(1) lgkmcnt(1)
	v_mfma_f32_16x16x4_f32 v[76:79], v105, v96, v[76:79]
	v_mfma_f32_16x16x4_f32 v[80:83], v105, v97, v[80:83]
	v_mfma_f32_16x16x4_f32 v[84:87], v105, v98, v[84:87]
	v_mfma_f32_16x16x4_f32 v[88:91], v105, v99, v[88:91]
	s_waitcnt vmcnt(0) lgkmcnt(0)
	v_mfma_f32_16x16x4_f32 v[76:79], v106, v100, v[76:79]
	v_mfma_f32_16x16x4_f32 v[80:83], v106, v101, v[80:83]
	v_mfma_f32_16x16x4_f32 v[84:87], v106, v102, v[84:87]
	v_mfma_f32_16x16x4_f32 v[88:91], v106, v103, v[88:91]
	s_nop 7
	ds_write_b32 v109, v76 offset:8192
	ds_write_b32 v109, v77 offset:8448
	ds_write_b32 v109, v78 offset:8704
	ds_write_b32 v109, v79 offset:8960
	ds_write_b32 v109, v80 offset:8196
	ds_write_b32 v109, v81 offset:8452
	ds_write_b32 v109, v82 offset:8708
	ds_write_b32 v109, v83 offset:8964
	ds_write_b32 v109, v84 offset:8200
	ds_write_b32 v109, v85 offset:8456
	ds_write_b32 v109, v86 offset:8712
	ds_write_b32 v109, v87 offset:8968
	s_nop 15
	s_nop 3
	ds_write_b32 v109, v88 offset:8204
	ds_write_b32 v109, v89 offset:8460
	ds_write_b32 v109, v90 offset:8716
	ds_write_b32 v109, v91 offset:8972
	s_waitcnt lgkmcnt(0)
	ds_read2st64_b32 v[62:63], v110 offset0:0 offset1:1
	ds_read2st64_b32 v[56:57], v110 offset0:2 offset1:3
	ds_read2st64_b32 v[50:51], v110 offset0:4 offset1:5
	ds_read2st64_b32 v[44:45], v110 offset0:6 offset1:7
	ds_read2st64_b32 v[38:39], v110 offset0:8 offset1:9
	ds_read2st64_b32 v[32:33], v110 offset0:10 offset1:11
	ds_read2st64_b32 v[26:27], v110 offset0:12 offset1:13
	ds_read2st64_b32 v[20:21], v110 offset0:14 offset1:15
	ds_read2st64_b32 v[64:65], v110 offset0:16 offset1:17
	ds_read2st64_b32 v[58:59], v110 offset0:18 offset1:19
	ds_read2st64_b32 v[52:53], v110 offset0:20 offset1:21
	ds_read2st64_b32 v[46:47], v110 offset0:22 offset1:23
	s_waitcnt lgkmcnt(0)
	ds_read2st64_b32 v[40:41], v110 offset0:24 offset1:25
	ds_read2st64_b32 v[34:35], v110 offset0:26 offset1:27
	ds_read2st64_b32 v[28:29], v110 offset0:28 offset1:29
	ds_read2st64_b32 v[22:23], v110 offset0:30 offset1:31
	ds_read2st64_b32 v[66:67], v110 offset0:32 offset1:33
	ds_read2st64_b32 v[60:61], v110 offset0:34 offset1:35
	ds_read2st64_b32 v[54:55], v110 offset0:36 offset1:37
	ds_read2st64_b32 v[48:49], v110 offset0:38 offset1:39
	ds_read2st64_b32 v[42:43], v110 offset0:40 offset1:41
	ds_read2st64_b32 v[36:37], v110 offset0:42 offset1:43
	ds_read2st64_b32 v[30:31], v110 offset0:44 offset1:45
	ds_read2st64_b32 v[24:25], v110 offset0:46 offset1:47
	s_waitcnt lgkmcnt(0)
	s_waitcnt lgkmcnt(0)
	s_ashr_i32 s19, s18, 31
	s_lshl_b64 s[0:1], s[18:19], 10
	v_lshlrev_b32_e32 v78, 1, v164
	v_or_b32_e32 v74, s0, v78
	v_mov_b32_e32 v75, s1
	s_or_b32 s0, s18, 1
	v_cvt_pk_bf16_f32 v17, v62, v1
	v_lshl_add_u64 v[76:77], s[12:13], 0, v[74:75]
	s_ashr_i32 s1, s0, 31
	global_store_short v[76:77], v17, off
	v_cvt_pk_bf16_f32 v17, v64, v1
	v_lshl_add_u64 v[76:77], s[14:15], 0, v[74:75]
	v_lshl_add_u64 v[74:75], s[92:93], 0, v[74:75]
	s_lshl_b64 s[0:1], s[0:1], 9
	global_store_short v[76:77], v17, off
	v_cvt_pk_bf16_f32 v17, v66, v1
	global_store_short v[74:75], v17, off
	v_lshl_add_u64 v[74:75], s[0:1], 0, v[164:165]
	v_cvt_pk_bf16_f32 v17, v63, v1
	v_lshlrev_b64 v[62:63], 1, v[74:75]
	s_or_b32 s0, s18, 2
	v_lshl_add_u64 v[74:75], s[12:13], 0, v[62:63]
	s_ashr_i32 s1, s0, 31
	global_store_short v[74:75], v17, off
	v_cvt_pk_bf16_f32 v17, v65, v1
	v_lshl_add_u64 v[64:65], s[14:15], 0, v[62:63]
	v_lshl_add_u64 v[62:63], s[92:93], 0, v[62:63]
	s_lshl_b64 s[0:1], s[0:1], 10
	global_store_short v[64:65], v17, off
	v_cvt_pk_bf16_f32 v17, v67, v1
	global_store_short v[62:63], v17, off
	v_or_b32_e32 v62, s0, v78
	v_mov_b32_e32 v63, s1
	s_or_b32 s0, s18, 3
	v_cvt_pk_bf16_f32 v17, v56, v1
	v_lshl_add_u64 v[64:65], s[12:13], 0, v[62:63]
	s_ashr_i32 s1, s0, 31
	global_store_short v[64:65], v17, off
	v_cvt_pk_bf16_f32 v17, v58, v1
	v_lshl_add_u64 v[64:65], s[14:15], 0, v[62:63]
	v_lshl_add_u64 v[62:63], s[92:93], 0, v[62:63]
	s_lshl_b64 s[0:1], s[0:1], 9
	global_store_short v[64:65], v17, off
	v_cvt_pk_bf16_f32 v17, v60, v1
	global_store_short v[62:63], v17, off
	v_lshl_add_u64 v[62:63], s[0:1], 0, v[164:165]
	v_cvt_pk_bf16_f32 v17, v57, v1
	v_lshlrev_b64 v[56:57], 1, v[62:63]
	s_or_b32 s0, s18, 4
	v_lshl_add_u64 v[62:63], s[12:13], 0, v[56:57]
	s_ashr_i32 s1, s0, 31
	global_store_short v[62:63], v17, off
	v_cvt_pk_bf16_f32 v17, v59, v1
	v_lshl_add_u64 v[58:59], s[14:15], 0, v[56:57]
	v_lshl_add_u64 v[56:57], s[92:93], 0, v[56:57]
	s_lshl_b64 s[0:1], s[0:1], 10
	global_store_short v[58:59], v17, off
	v_cvt_pk_bf16_f32 v17, v61, v1
	global_store_short v[56:57], v17, off
	v_or_b32_e32 v56, s0, v78
	v_mov_b32_e32 v57, s1
	s_or_b32 s0, s18, 5
	v_cvt_pk_bf16_f32 v17, v50, v1
	v_lshl_add_u64 v[58:59], s[12:13], 0, v[56:57]
	s_ashr_i32 s1, s0, 31
	global_store_short v[58:59], v17, off
	v_cvt_pk_bf16_f32 v17, v52, v1
	v_lshl_add_u64 v[58:59], s[14:15], 0, v[56:57]
	v_lshl_add_u64 v[56:57], s[92:93], 0, v[56:57]
	s_lshl_b64 s[0:1], s[0:1], 9
	global_store_short v[58:59], v17, off
	v_cvt_pk_bf16_f32 v17, v54, v1
	global_store_short v[56:57], v17, off
	v_lshl_add_u64 v[56:57], s[0:1], 0, v[164:165]
	v_cvt_pk_bf16_f32 v17, v51, v1
	v_lshlrev_b64 v[50:51], 1, v[56:57]
	s_or_b32 s0, s18, 6
	v_lshl_add_u64 v[56:57], s[12:13], 0, v[50:51]
	s_ashr_i32 s1, s0, 31
	global_store_short v[56:57], v17, off
	v_cvt_pk_bf16_f32 v17, v53, v1
	v_lshl_add_u64 v[52:53], s[14:15], 0, v[50:51]
	v_lshl_add_u64 v[50:51], s[92:93], 0, v[50:51]
	s_lshl_b64 s[0:1], s[0:1], 10
	global_store_short v[52:53], v17, off
	v_cvt_pk_bf16_f32 v17, v55, v1
	global_store_short v[50:51], v17, off
	v_or_b32_e32 v50, s0, v78
	v_mov_b32_e32 v51, s1
	s_or_b32 s0, s18, 7
	v_cvt_pk_bf16_f32 v17, v44, v1
	v_lshl_add_u64 v[52:53], s[12:13], 0, v[50:51]
	s_ashr_i32 s1, s0, 31
	global_store_short v[52:53], v17, off
	v_cvt_pk_bf16_f32 v17, v46, v1
	v_lshl_add_u64 v[52:53], s[14:15], 0, v[50:51]
	v_lshl_add_u64 v[50:51], s[92:93], 0, v[50:51]
	s_lshl_b64 s[0:1], s[0:1], 9
	global_store_short v[52:53], v17, off
	v_cvt_pk_bf16_f32 v17, v48, v1
	global_store_short v[50:51], v17, off
	v_lshl_add_u64 v[50:51], s[0:1], 0, v[164:165]
	v_cvt_pk_bf16_f32 v17, v45, v1
	v_lshlrev_b64 v[44:45], 1, v[50:51]
	s_or_b32 s0, s18, 8
	v_lshl_add_u64 v[50:51], s[12:13], 0, v[44:45]
	s_ashr_i32 s1, s0, 31
	global_store_short v[50:51], v17, off
	v_cvt_pk_bf16_f32 v17, v47, v1
	v_lshl_add_u64 v[46:47], s[14:15], 0, v[44:45]
	v_lshl_add_u64 v[44:45], s[92:93], 0, v[44:45]
	s_lshl_b64 s[0:1], s[0:1], 10
	global_store_short v[46:47], v17, off
	v_cvt_pk_bf16_f32 v17, v49, v1
	global_store_short v[44:45], v17, off
	v_or_b32_e32 v44, s0, v78
	v_mov_b32_e32 v45, s1
	s_or_b32 s0, s18, 9
	v_cvt_pk_bf16_f32 v17, v38, v1
	v_lshl_add_u64 v[46:47], s[12:13], 0, v[44:45]
	s_ashr_i32 s1, s0, 31
	global_store_short v[46:47], v17, off
	v_cvt_pk_bf16_f32 v17, v40, v1
	v_lshl_add_u64 v[46:47], s[14:15], 0, v[44:45]
	v_lshl_add_u64 v[44:45], s[92:93], 0, v[44:45]
	s_lshl_b64 s[0:1], s[0:1], 9
	global_store_short v[46:47], v17, off
	v_cvt_pk_bf16_f32 v17, v42, v1
	global_store_short v[44:45], v17, off
	v_lshl_add_u64 v[44:45], s[0:1], 0, v[164:165]
	v_cvt_pk_bf16_f32 v17, v39, v1
	v_lshlrev_b64 v[38:39], 1, v[44:45]
	s_or_b32 s0, s18, 10
	v_lshl_add_u64 v[44:45], s[12:13], 0, v[38:39]
	s_ashr_i32 s1, s0, 31
	global_store_short v[44:45], v17, off
	v_cvt_pk_bf16_f32 v17, v41, v1
	v_lshl_add_u64 v[40:41], s[14:15], 0, v[38:39]
	v_lshl_add_u64 v[38:39], s[92:93], 0, v[38:39]
	s_lshl_b64 s[0:1], s[0:1], 10
	global_store_short v[40:41], v17, off
	v_cvt_pk_bf16_f32 v17, v43, v1
	global_store_short v[38:39], v17, off
	v_or_b32_e32 v38, s0, v78
	v_mov_b32_e32 v39, s1
	s_or_b32 s0, s18, 11
	v_cvt_pk_bf16_f32 v17, v32, v1
	v_lshl_add_u64 v[40:41], s[12:13], 0, v[38:39]
	s_ashr_i32 s1, s0, 31
	global_store_short v[40:41], v17, off
	v_cvt_pk_bf16_f32 v17, v34, v1
	v_lshl_add_u64 v[40:41], s[14:15], 0, v[38:39]
	v_lshl_add_u64 v[38:39], s[92:93], 0, v[38:39]
	s_lshl_b64 s[0:1], s[0:1], 9
	global_store_short v[40:41], v17, off
	v_cvt_pk_bf16_f32 v17, v36, v1
	global_store_short v[38:39], v17, off
	v_lshl_add_u64 v[38:39], s[0:1], 0, v[164:165]
	v_cvt_pk_bf16_f32 v17, v33, v1
	v_lshlrev_b64 v[32:33], 1, v[38:39]
	s_or_b32 s0, s18, 12
	v_lshl_add_u64 v[38:39], s[12:13], 0, v[32:33]
	s_ashr_i32 s1, s0, 31
	global_store_short v[38:39], v17, off
	v_cvt_pk_bf16_f32 v17, v35, v1
	v_lshl_add_u64 v[34:35], s[14:15], 0, v[32:33]
	v_lshl_add_u64 v[32:33], s[92:93], 0, v[32:33]
	s_lshl_b64 s[0:1], s[0:1], 10
	global_store_short v[34:35], v17, off
	v_cvt_pk_bf16_f32 v17, v37, v1
	global_store_short v[32:33], v17, off
	v_or_b32_e32 v32, s0, v78
	v_mov_b32_e32 v33, s1
	s_or_b32 s0, s18, 13
	v_cvt_pk_bf16_f32 v17, v26, v1
	v_lshl_add_u64 v[34:35], s[12:13], 0, v[32:33]
	s_ashr_i32 s1, s0, 31
	global_store_short v[34:35], v17, off
	v_cvt_pk_bf16_f32 v17, v28, v1
	v_lshl_add_u64 v[34:35], s[14:15], 0, v[32:33]
	v_lshl_add_u64 v[32:33], s[92:93], 0, v[32:33]
	s_lshl_b64 s[0:1], s[0:1], 9
	global_store_short v[34:35], v17, off
	v_cvt_pk_bf16_f32 v17, v30, v1
	global_store_short v[32:33], v17, off
	v_lshl_add_u64 v[32:33], s[0:1], 0, v[164:165]
	v_cvt_pk_bf16_f32 v17, v27, v1
	v_lshlrev_b64 v[26:27], 1, v[32:33]
	s_or_b32 s0, s18, 14
	v_lshl_add_u64 v[32:33], s[12:13], 0, v[26:27]
	s_ashr_i32 s1, s0, 31
	global_store_short v[32:33], v17, off
	v_cvt_pk_bf16_f32 v17, v29, v1
	v_lshl_add_u64 v[28:29], s[14:15], 0, v[26:27]
	v_lshl_add_u64 v[26:27], s[92:93], 0, v[26:27]
	s_lshl_b64 s[0:1], s[0:1], 10
	global_store_short v[28:29], v17, off
	v_cvt_pk_bf16_f32 v17, v31, v1
	global_store_short v[26:27], v17, off
	v_or_b32_e32 v26, s0, v78
	v_mov_b32_e32 v27, s1
	s_or_b32 s0, s18, 15
	v_cvt_pk_bf16_f32 v17, v20, v1
	v_lshl_add_u64 v[28:29], s[12:13], 0, v[26:27]
	s_ashr_i32 s1, s0, 31
	global_store_short v[28:29], v17, off
	v_cvt_pk_bf16_f32 v17, v22, v1
	v_lshl_add_u64 v[28:29], s[14:15], 0, v[26:27]
	v_lshl_add_u64 v[26:27], s[92:93], 0, v[26:27]
	s_lshl_b64 s[0:1], s[0:1], 9
	global_store_short v[28:29], v17, off
	v_cvt_pk_bf16_f32 v17, v24, v1
	global_store_short v[26:27], v17, off
	v_lshl_add_u64 v[26:27], s[0:1], 0, v[164:165]
	v_cvt_pk_bf16_f32 v17, v21, v1
	v_lshlrev_b64 v[20:21], 1, v[26:27]
	v_lshl_add_u64 v[26:27], s[12:13], 0, v[20:21]
	s_add_i32 s48, s48, s30
	global_store_short v[26:27], v17, off
	v_cvt_pk_bf16_f32 v17, v23, v1
	v_lshl_add_u64 v[22:23], s[14:15], 0, v[20:21]
	v_lshl_add_u64 v[20:21], s[92:93], 0, v[20:21]
	s_cmpk_gt_i32 s48, 0x3ff
	global_store_short v[22:23], v17, off
	v_cvt_pk_bf16_f32 v17, v25, v1
	global_store_short v[20:21], v17, off
	s_barrier
	s_cbranch_scc0 .LBB0_944

.LBB0_1180:
	s_lshl_b32 s45, s44, 4
	s_mov_b32 s6, 0xffffde00
	s_mov_b32 s7, -1
	s_mov_b32 s24, 0x2200
	s_mov_b32 s25, 0
	v_lshlrev_b32_e32 v98, 1, v100
	v_readlane_b32 s10, v255, 33
	v_readlane_b32 s11, v255, 34
	v_and_b32_e32 v151, 63, v164
	v_lshrrev_b32_e32 v152, 6, v164
	v_lshlrev_b32_e32 v148, 2, v151
	v_lshrrev_b32_e32 v153, 4, v151
	v_and_b32_e32 v154, 15, v151
	v_lshlrev_b32_e32 v149, 11, v153
	v_lshl_add_u32 v149, v152, 8, v149
	v_lshl_add_u32 v149, v154, 4, v149
	v_lshlrev_b32_e32 v150, 13, v153
	v_lshl_add_u32 v150, v152, 8, v150
	v_lshl_add_u32 v150, v154, 4, v150
	v_add_u32_e32 v150, 0x2000, v150
	global_load_dwordx4 v[136:139], v149, s[10:11]
	v_add_u32_e32 v149, 0x2000, v149
	global_load_dwordx4 v[140:143], v149, s[10:11]
	v_add_u32_e32 v149, 0x2000, v149
	global_load_dword v88, v[102:103], off
	global_load_dword v89, v[104:105], off
	v_or_b32_e32 v176, s45, v101
	v_mov_b64_e32 v[180:181], s[38:39]
	v_mad_i64_i32 v[180:181], s[0:1], v176, s35, v[180:181]
	v_lshl_add_u64 v[180:181], v[180:181], 0, v[98:99]
	v_lshl_add_u64 v[180:181], v[180:181], 0, s[20:21]
	v_lshl_add_u64 v[188:189], v[180:181], 0, s[6:7]
	v_lshl_add_u64 v[190:191], v[180:181], 0, s[24:25]
	global_load_ushort v192, v[180:181], off
	global_load_ushort v196, v[188:189], off
	global_load_ushort v200, v[190:191], off
	v_or_b32_e32 v177, s45, v120
	v_mov_b64_e32 v[182:183], s[38:39]
	v_mad_i64_i32 v[182:183], s[0:1], v177, s35, v[182:183]
	v_lshl_add_u64 v[182:183], v[182:183], 0, v[98:99]
	v_lshl_add_u64 v[182:183], v[182:183], 0, s[20:21]
	v_lshl_add_u64 v[188:189], v[182:183], 0, s[6:7]
	v_lshl_add_u64 v[190:191], v[182:183], 0, s[24:25]
	global_load_ushort v193, v[182:183], off
	global_load_ushort v197, v[188:189], off
	global_load_ushort v201, v[190:191], off
	v_or_b32_e32 v178, s45, v122
	v_mov_b64_e32 v[184:185], s[38:39]
	v_mad_i64_i32 v[184:185], s[0:1], v178, s35, v[184:185]
	v_lshl_add_u64 v[184:185], v[184:185], 0, v[98:99]
	v_lshl_add_u64 v[184:185], v[184:185], 0, s[20:21]
	v_lshl_add_u64 v[188:189], v[184:185], 0, s[6:7]
	v_lshl_add_u64 v[190:191], v[184:185], 0, s[24:25]
	global_load_ushort v194, v[184:185], off
	global_load_ushort v198, v[188:189], off
	global_load_ushort v202, v[190:191], off
	v_or_b32_e32 v179, s45, v123
	v_mov_b64_e32 v[186:187], s[38:39]
	v_mad_i64_i32 v[186:187], s[0:1], v179, s35, v[186:187]
	v_lshl_add_u64 v[186:187], v[186:187], 0, v[98:99]
	v_lshl_add_u64 v[186:187], v[186:187], 0, s[20:21]
	v_lshl_add_u64 v[188:189], v[186:187], 0, s[6:7]
	v_lshl_add_u64 v[190:191], v[186:187], 0, s[24:25]
	global_load_ushort v195, v[186:187], off
	global_load_ushort v199, v[188:189], off
	global_load_ushort v203, v[190:191], off
	s_waitcnt vmcnt(0)
	v_and_b32_e32 v90, v127, v176
	v_lshlrev_b32_e32 v91, 16, v192
	v_lshlrev_b32_e32 v92, 16, v196
	v_lshlrev_b32_e32 v93, 16, v200
	v_cmp_ne_u32_e32 vcc, 0, v90
	s_nop 1
	v_cndmask_b32_e32 v92, 0, v92, vcc
	v_cmp_ne_u32_e32 vcc, s40, v90
	s_nop 1
	v_cndmask_b32_e32 v93, 0, v93, vcc
	v_sub_f32_e32 v92, v92, v91
	v_sub_f32_e32 v93, v93, v91
	v_mul_f32_e32 v92, v92, v88
	v_mul_f32_e32 v93, v93, v89
	v_add_f32_e32 v92, v92, v91
	v_add_f32_e32 v92, v92, v93
	v_mul_f32_e32 v92, 0xbfb8aa3b, v92
	v_exp_f32_e32 v92, v92
	s_nop 0
	v_add_f32_e32 v95, 1.0, v92
	v_div_scale_f32 v93, s[0:1], v95, v95, 1.0
	v_rcp_f32_e32 v94, v93
	v_div_scale_f32 v112, vcc, 1.0, v95, 1.0
	v_fma_f32 v113, -v93, v94, 1.0
	v_fmac_f32_e32 v94, v113, v94
	v_mul_f32_e32 v113, v112, v94
	v_fma_f32 v114, -v93, v113, v112
	v_fmac_f32_e32 v113, v114, v94
	v_fma_f32 v93, -v93, v113, v112
	v_div_fmas_f32 v112, v93, v94, v113
	v_div_fixup_f32 v92, v112, v95, 1.0
	ds_write_b32 v109, v92
	v_and_b32_e32 v90, v127, v177
	v_lshlrev_b32_e32 v91, 16, v193
	v_lshlrev_b32_e32 v92, 16, v197
	v_lshlrev_b32_e32 v93, 16, v201
	v_cmp_ne_u32_e32 vcc, 0, v90
	s_nop 1
	v_cndmask_b32_e32 v92, 0, v92, vcc
	v_cmp_ne_u32_e32 vcc, s40, v90
	s_nop 1
	v_cndmask_b32_e32 v93, 0, v93, vcc
	v_sub_f32_e32 v92, v92, v91
	v_sub_f32_e32 v93, v93, v91
	v_mul_f32_e32 v92, v92, v88
	v_mul_f32_e32 v93, v93, v89
	v_add_f32_e32 v92, v92, v91
	v_add_f32_e32 v92, v92, v93
	v_mul_f32_e32 v92, 0xbfb8aa3b, v92
	v_exp_f32_e32 v92, v92
	s_nop 0
	v_add_f32_e32 v95, 1.0, v92
	v_div_scale_f32 v93, s[0:1], v95, v95, 1.0
	v_rcp_f32_e32 v94, v93
	v_div_scale_f32 v112, vcc, 1.0, v95, 1.0
	v_fma_f32 v113, -v93, v94, 1.0
	v_fmac_f32_e32 v94, v113, v94
	v_mul_f32_e32 v113, v112, v94
	v_fma_f32 v114, -v93, v113, v112
	v_fmac_f32_e32 v113, v114, v94
	v_fma_f32 v93, -v93, v113, v112
	v_div_fmas_f32 v112, v93, v94, v113
	v_div_fixup_f32 v92, v112, v95, 1.0
	ds_write_b32 v121, v92
	v_and_b32_e32 v90, v127, v178
	v_lshlrev_b32_e32 v91, 16, v194
	v_lshlrev_b32_e32 v92, 16, v198
	v_lshlrev_b32_e32 v93, 16, v202
	v_cmp_ne_u32_e32 vcc, 0, v90
	s_nop 1
	v_cndmask_b32_e32 v92, 0, v92, vcc
	v_cmp_ne_u32_e32 vcc, s40, v90
	s_nop 1
	v_cndmask_b32_e32 v93, 0, v93, vcc
	v_sub_f32_e32 v92, v92, v91
	v_sub_f32_e32 v93, v93, v91
	v_mul_f32_e32 v92, v92, v88
	v_mul_f32_e32 v93, v93, v89
	v_add_f32_e32 v92, v92, v91
	v_add_f32_e32 v92, v92, v93
	v_mul_f32_e32 v92, 0xbfb8aa3b, v92
	v_exp_f32_e32 v92, v92
	s_nop 0
	v_add_f32_e32 v95, 1.0, v92
	v_div_scale_f32 v93, s[0:1], v95, v95, 1.0
	v_rcp_f32_e32 v94, v93
	v_div_scale_f32 v112, vcc, 1.0, v95, 1.0
	v_fma_f32 v113, -v93, v94, 1.0
	v_fmac_f32_e32 v94, v113, v94
	v_mul_f32_e32 v113, v112, v94
	v_fma_f32 v114, -v93, v113, v112
	v_fmac_f32_e32 v113, v114, v94
	v_fma_f32 v93, -v93, v113, v112
	v_div_fmas_f32 v112, v93, v94, v113
	v_div_fixup_f32 v92, v112, v95, 1.0
	ds_write_b32 v109, v92 offset:32
	v_and_b32_e32 v90, v127, v179
	v_lshlrev_b32_e32 v91, 16, v195
	v_lshlrev_b32_e32 v92, 16, v199
	v_lshlrev_b32_e32 v93, 16, v203
	v_cmp_ne_u32_e32 vcc, 0, v90
	s_nop 1
	v_cndmask_b32_e32 v92, 0, v92, vcc
	v_cmp_ne_u32_e32 vcc, s40, v90
	s_nop 1
	v_cndmask_b32_e32 v93, 0, v93, vcc
	v_sub_f32_e32 v92, v92, v91
	v_sub_f32_e32 v93, v93, v91
	v_mul_f32_e32 v92, v92, v88
	v_mul_f32_e32 v93, v93, v89
	v_add_f32_e32 v92, v92, v91
	v_add_f32_e32 v92, v92, v93
	v_mul_f32_e32 v92, 0xbfb8aa3b, v92
	v_exp_f32_e32 v92, v92
	s_nop 0
	v_add_f32_e32 v95, 1.0, v92
	v_div_scale_f32 v93, s[0:1], v95, v95, 1.0
	v_rcp_f32_e32 v94, v93
	v_div_scale_f32 v112, vcc, 1.0, v95, 1.0
	v_fma_f32 v113, -v93, v94, 1.0
	v_fmac_f32_e32 v94, v113, v94
	v_mul_f32_e32 v113, v112, v94
	v_fma_f32 v114, -v93, v113, v112
	v_fmac_f32_e32 v113, v114, v94
	v_fma_f32 v93, -v93, v113, v112
	v_div_fmas_f32 v112, v93, v94, v113
	v_div_fixup_f32 v92, v112, v95, 1.0
	ds_write_b32 v124, v92
	v_mov_b32_e32 v88, 0
	v_mov_b32_e32 v89, 0
	v_mov_b32_e32 v90, 0
	v_mov_b32_e32 v91, 0
	v_mov_b32_e32 v92, 0
	v_mov_b32_e32 v93, 0
	v_mov_b32_e32 v94, 0
	v_mov_b32_e32 v95, 0
	v_mov_b32_e32 v112, 0
	v_mov_b32_e32 v113, 0
	v_mov_b32_e32 v114, 0
	v_mov_b32_e32 v115, 0
	v_mov_b32_e32 v116, 0
	v_mov_b32_e32 v117, 0
	v_mov_b32_e32 v118, 0
	v_mov_b32_e32 v119, 0
	s_mov_b32 s6, 0
	s_mov_b64 s[0:1], 0
	s_waitcnt lgkmcnt(0)
	s_barrier
	ds_read_b32 v132, v148 offset:0
	ds_read_b32 v133, v148 offset:256
	global_load_dwordx4 v[144:147], v149, s[10:11]
	v_add_u32_e32 v149, 0x2000, v149
	ds_read_b32 v134, v148 offset:512
	s_waitcnt vmcnt(2) lgkmcnt(2)
	v_mfma_f32_16x16x4_f32 v[88:91], v132, v136, v[88:91]
	v_mfma_f32_16x16x4_f32 v[92:95], v132, v137, v[92:95]
	v_mfma_f32_16x16x4_f32 v[112:115], v132, v138, v[112:115]
	v_mfma_f32_16x16x4_f32 v[116:119], v132, v139, v[116:119]
	global_load_dwordx4 v[136:139], v149, s[10:11]
	v_add_u32_e32 v149, 0x2000, v149
	ds_read_b32 v132, v148 offset:768
	s_waitcnt vmcnt(2) lgkmcnt(2)
	v_mfma_f32_16x16x4_f32 v[88:91], v133, v140, v[88:91]
	v_mfma_f32_16x16x4_f32 v[92:95], v133, v141, v[92:95]
	v_mfma_f32_16x16x4_f32 v[112:115], v133, v142, v[112:115]
	v_mfma_f32_16x16x4_f32 v[116:119], v133, v143, v[116:119]
	global_load_dwordx4 v[140:143], v149, s[10:11]
	v_add_u32_e32 v149, 0x2000, v149
	ds_read_b32 v133, v148 offset:1024
	s_waitcnt vmcnt(2) lgkmcnt(2)
	v_mfma_f32_16x16x4_f32 v[88:91], v134, v144, v[88:91]
	v_mfma_f32_16x16x4_f32 v[92:95], v134, v145, v[92:95]
	v_mfma_f32_16x16x4_f32 v[112:115], v134, v146, v[112:115]
	v_mfma_f32_16x16x4_f32 v[116:119], v134, v147, v[116:119]
	global_load_dwordx4 v[144:147], v149, s[10:11]
	v_add_u32_e32 v149, 0x2000, v149
	ds_read_b32 v134, v148 offset:1280
	s_waitcnt vmcnt(2) lgkmcnt(2)
	v_mfma_f32_16x16x4_f32 v[88:91], v132, v136, v[88:91]
	v_mfma_f32_16x16x4_f32 v[92:95], v132, v137, v[92:95]
	v_mfma_f32_16x16x4_f32 v[112:115], v132, v138, v[112:115]
	v_mfma_f32_16x16x4_f32 v[116:119], v132, v139, v[116:119]
	global_load_dwordx4 v[136:139], v149, s[10:11]
	v_add_u32_e32 v149, 0x2000, v149
	ds_read_b32 v132, v148 offset:1536
	s_waitcnt vmcnt(2) lgkmcnt(2)
	v_mfma_f32_16x16x4_f32 v[88:91], v133, v140, v[88:91]
	v_mfma_f32_16x16x4_f32 v[92:95], v133, v141, v[92:95]
	v_mfma_f32_16x16x4_f32 v[112:115], v133, v142, v[112:115]
	v_mfma_f32_16x16x4_f32 v[116:119], v133, v143, v[116:119]
	global_load_dwordx4 v[140:143], v149, s[10:11]
	v_add_u32_e32 v149, 0x2000, v149
	ds_read_b32 v133, v148 offset:1792
	s_waitcnt vmcnt(2) lgkmcnt(2)
	v_mfma_f32_16x16x4_f32 v[88:91], v134, v144, v[88:91]
	v_mfma_f32_16x16x4_f32 v[92:95], v134, v145, v[92:95]
	v_mfma_f32_16x16x4_f32 v[112:115], v134, v146, v[112:115]
	v_mfma_f32_16x16x4_f32 v[116:119], v134, v147, v[116:119]
	global_load_dwordx4 v[144:147], v149, s[10:11]
	v_add_u32_e32 v149, 0x2000, v149
	ds_read_b32 v134, v148 offset:2048
	s_waitcnt vmcnt(2) lgkmcnt(2)
	v_mfma_f32_16x16x4_f32 v[88:91], v132, v136, v[88:91]
	v_mfma_f32_16x16x4_f32 v[92:95], v132, v137, v[92:95]
	v_mfma_f32_16x16x4_f32 v[112:115], v132, v138, v[112:115]
	v_mfma_f32_16x16x4_f32 v[116:119], v132, v139, v[116:119]
	global_load_dwordx4 v[136:139], v149, s[10:11]
	v_add_u32_e32 v149, 0x2000, v149
	ds_read_b32 v132, v148 offset:2304
	s_waitcnt vmcnt(2) lgkmcnt(2)
	v_mfma_f32_16x16x4_f32 v[88:91], v133, v140, v[88:91]
	v_mfma_f32_16x16x4_f32 v[92:95], v133, v141, v[92:95]
	v_mfma_f32_16x16x4_f32 v[112:115], v133, v142, v[112:115]
	v_mfma_f32_16x16x4_f32 v[116:119], v133, v143, v[116:119]
	global_load_dwordx4 v[140:143], v149, s[10:11]
	v_add_u32_e32 v149, 0x2000, v149
	ds_read_b32 v133, v148 offset:2560
	s_waitcnt vmcnt(2) lgkmcnt(2)
	v_mfma_f32_16x16x4_f32 v[88:91], v134, v144, v[88:91]
	v_mfma_f32_16x16x4_f32 v[92:95], v134, v145, v[92:95]
	v_mfma_f32_16x16x4_f32 v[112:115], v134, v146, v[112:115]
	v_mfma_f32_16x16x4_f32 v[116:119], v134, v147, v[116:119]
	global_load_dwordx4 v[144:147], v149, s[10:11]
	v_add_u32_e32 v149, 0x2000, v149
	ds_read_b32 v134, v148 offset:2816
	s_waitcnt vmcnt(2) lgkmcnt(2)
	v_mfma_f32_16x16x4_f32 v[88:91], v132, v136, v[88:91]
	v_mfma_f32_16x16x4_f32 v[92:95], v132, v137, v[92:95]
	v_mfma_f32_16x16x4_f32 v[112:115], v132, v138, v[112:115]
	v_mfma_f32_16x16x4_f32 v[116:119], v132, v139, v[116:119]
	global_load_dwordx4 v[136:139], v149, s[10:11]
	v_add_u32_e32 v149, 0x2000, v149
	ds_read_b32 v132, v148 offset:3072
	s_waitcnt vmcnt(2) lgkmcnt(2)
	v_mfma_f32_16x16x4_f32 v[88:91], v133, v140, v[88:91]
	v_mfma_f32_16x16x4_f32 v[92:95], v133, v141, v[92:95]
	v_mfma_f32_16x16x4_f32 v[112:115], v133, v142, v[112:115]
	v_mfma_f32_16x16x4_f32 v[116:119], v133, v143, v[116:119]
	global_load_dwordx4 v[140:143], v149, s[10:11]
	v_add_u32_e32 v149, 0x2000, v149
	ds_read_b32 v133, v148 offset:3328
	s_waitcnt vmcnt(2) lgkmcnt(2)
	v_mfma_f32_16x16x4_f32 v[88:91], v134, v144, v[88:91]
	v_mfma_f32_16x16x4_f32 v[92:95], v134, v145, v[92:95]
	v_mfma_f32_16x16x4_f32 v[112:115], v134, v146, v[112:115]
	v_mfma_f32_16x16x4_f32 v[116:119], v134, v147, v[116:119]
	global_load_dwordx4 v[144:147], v149, s[10:11]
	v_add_u32_e32 v149, 0x2000, v149
	ds_read_b32 v134, v148 offset:3584
	s_waitcnt vmcnt(2) lgkmcnt(2)
	v_mfma_f32_16x16x4_f32 v[88:91], v132, v136, v[88:91]
	v_mfma_f32_16x16x4_f32 v[92:95], v132, v137, v[92:95]
	v_mfma_f32_16x16x4_f32 v[112:115], v132, v138, v[112:115]
	v_mfma_f32_16x16x4_f32 v[116:119], v132, v139, v[116:119]
	global_load_dwordx4 v[136:139], v149, s[10:11]
	v_add_u32_e32 v149, 0x2000, v149
	ds_read_b32 v132, v148 offset:3840
	s_waitcnt vmcnt(2) lgkmcnt(2)
	v_mfma_f32_16x16x4_f32 v[88:91], v133, v140, v[88:91]
	v_mfma_f32_16x16x4_f32 v[92:95], v133, v141, v[92:95]
	v_mfma_f32_16x16x4_f32 v[112:115], v133, v142, v[112:115]
	v_mfma_f32_16x16x4_f32 v[116:119], v133, v143, v[116:119]
	global_load_dwordx4 v[140:143], v149, s[10:11]
	v_add_u32_e32 v149, 0x2000, v149
	ds_read_b32 v133, v148 offset:4096
	s_waitcnt vmcnt(2) lgkmcnt(2)
	v_mfma_f32_16x16x4_f32 v[88:91], v134, v144, v[88:91]
	v_mfma_f32_16x16x4_f32 v[92:95], v134, v145, v[92:95]
	v_mfma_f32_16x16x4_f32 v[112:115], v134, v146, v[112:115]
	v_mfma_f32_16x16x4_f32 v[116:119], v134, v147, v[116:119]
	global_load_dwordx4 v[144:147], v149, s[10:11]
	v_add_u32_e32 v149, 0x2000, v149
	ds_read_b32 v134, v148 offset:4352
	s_waitcnt vmcnt(2) lgkmcnt(2)
	v_mfma_f32_16x16x4_f32 v[88:91], v132, v136, v[88:91]
	v_mfma_f32_16x16x4_f32 v[92:95], v132, v137, v[92:95]
	v_mfma_f32_16x16x4_f32 v[112:115], v132, v138, v[112:115]
	v_mfma_f32_16x16x4_f32 v[116:119], v132, v139, v[116:119]
	global_load_dwordx4 v[136:139], v149, s[10:11]
	v_add_u32_e32 v149, 0x2000, v149
	ds_read_b32 v132, v148 offset:4608
	s_waitcnt vmcnt(2) lgkmcnt(2)
	v_mfma_f32_16x16x4_f32 v[88:91], v133, v140, v[88:91]
	v_mfma_f32_16x16x4_f32 v[92:95], v133, v141, v[92:95]
	v_mfma_f32_16x16x4_f32 v[112:115], v133, v142, v[112:115]
	v_mfma_f32_16x16x4_f32 v[116:119], v133, v143, v[116:119]
	global_load_dwordx4 v[140:143], v149, s[10:11]
	v_add_u32_e32 v149, 0x2000, v149
	ds_read_b32 v133, v148 offset:4864
	s_waitcnt vmcnt(2) lgkmcnt(2)
	v_mfma_f32_16x16x4_f32 v[88:91], v134, v144, v[88:91]
	v_mfma_f32_16x16x4_f32 v[92:95], v134, v145, v[92:95]
	v_mfma_f32_16x16x4_f32 v[112:115], v134, v146, v[112:115]
	v_mfma_f32_16x16x4_f32 v[116:119], v134, v147, v[116:119]
	global_load_dwordx4 v[144:147], v149, s[10:11]
	v_add_u32_e32 v149, 0x2000, v149
	ds_read_b32 v134, v148 offset:5120
	s_waitcnt vmcnt(2) lgkmcnt(2)
	v_mfma_f32_16x16x4_f32 v[88:91], v132, v136, v[88:91]
	v_mfma_f32_16x16x4_f32 v[92:95], v132, v137, v[92:95]
	v_mfma_f32_16x16x4_f32 v[112:115], v132, v138, v[112:115]
	v_mfma_f32_16x16x4_f32 v[116:119], v132, v139, v[116:119]
	global_load_dwordx4 v[136:139], v149, s[10:11]
	v_add_u32_e32 v149, 0x2000, v149
	ds_read_b32 v132, v148 offset:5376
	s_waitcnt vmcnt(2) lgkmcnt(2)
	v_mfma_f32_16x16x4_f32 v[88:91], v133, v140, v[88:91]
	v_mfma_f32_16x16x4_f32 v[92:95], v133, v141, v[92:95]
	v_mfma_f32_16x16x4_f32 v[112:115], v133, v142, v[112:115]
	v_mfma_f32_16x16x4_f32 v[116:119], v133, v143, v[116:119]
	global_load_dwordx4 v[140:143], v149, s[10:11]
	v_add_u32_e32 v149, 0x2000, v149
	ds_read_b32 v133, v148 offset:5632
	s_waitcnt vmcnt(2) lgkmcnt(2)
	v_mfma_f32_16x16x4_f32 v[88:91], v134, v144, v[88:91]
	v_mfma_f32_16x16x4_f32 v[92:95], v134, v145, v[92:95]
	v_mfma_f32_16x16x4_f32 v[112:115], v134, v146, v[112:115]
	v_mfma_f32_16x16x4_f32 v[116:119], v134, v147, v[116:119]
	global_load_dwordx4 v[144:147], v149, s[10:11]
	v_add_u32_e32 v149, 0x2000, v149
	ds_read_b32 v134, v148 offset:5888
	s_waitcnt vmcnt(2) lgkmcnt(2)
	v_mfma_f32_16x16x4_f32 v[88:91], v132, v136, v[88:91]
	v_mfma_f32_16x16x4_f32 v[92:95], v132, v137, v[92:95]
	v_mfma_f32_16x16x4_f32 v[112:115], v132, v138, v[112:115]
	v_mfma_f32_16x16x4_f32 v[116:119], v132, v139, v[116:119]
	global_load_dwordx4 v[136:139], v149, s[10:11]
	v_add_u32_e32 v149, 0x2000, v149
	ds_read_b32 v132, v148 offset:6144
	s_waitcnt vmcnt(2) lgkmcnt(2)
	v_mfma_f32_16x16x4_f32 v[88:91], v133, v140, v[88:91]
	v_mfma_f32_16x16x4_f32 v[92:95], v133, v141, v[92:95]
	v_mfma_f32_16x16x4_f32 v[112:115], v133, v142, v[112:115]
	v_mfma_f32_16x16x4_f32 v[116:119], v133, v143, v[116:119]
	global_load_dwordx4 v[140:143], v149, s[10:11]
	v_add_u32_e32 v149, 0x2000, v149
	ds_read_b32 v133, v148 offset:6400
	s_waitcnt vmcnt(2) lgkmcnt(2)
	v_mfma_f32_16x16x4_f32 v[88:91], v134, v144, v[88:91]
	v_mfma_f32_16x16x4_f32 v[92:95], v134, v145, v[92:95]
	v_mfma_f32_16x16x4_f32 v[112:115], v134, v146, v[112:115]
	v_mfma_f32_16x16x4_f32 v[116:119], v134, v147, v[116:119]
	global_load_dwordx4 v[144:147], v149, s[10:11]
	v_add_u32_e32 v149, 0x2000, v149
	ds_read_b32 v134, v148 offset:6656
	s_waitcnt vmcnt(2) lgkmcnt(2)
	v_mfma_f32_16x16x4_f32 v[88:91], v132, v136, v[88:91]
	v_mfma_f32_16x16x4_f32 v[92:95], v132, v137, v[92:95]
	v_mfma_f32_16x16x4_f32 v[112:115], v132, v138, v[112:115]
	v_mfma_f32_16x16x4_f32 v[116:119], v132, v139, v[116:119]
	global_load_dwordx4 v[136:139], v149, s[10:11]
	v_add_u32_e32 v149, 0x2000, v149
	ds_read_b32 v132, v148 offset:6912
	s_waitcnt vmcnt(2) lgkmcnt(2)
	v_mfma_f32_16x16x4_f32 v[88:91], v133, v140, v[88:91]
	v_mfma_f32_16x16x4_f32 v[92:95], v133, v141, v[92:95]
	v_mfma_f32_16x16x4_f32 v[112:115], v133, v142, v[112:115]
	v_mfma_f32_16x16x4_f32 v[116:119], v133, v143, v[116:119]
	global_load_dwordx4 v[140:143], v149, s[10:11]
	v_add_u32_e32 v149, 0x2000, v149
	ds_read_b32 v133, v148 offset:7168
	s_waitcnt vmcnt(2) lgkmcnt(2)
	v_mfma_f32_16x16x4_f32 v[88:91], v134, v144, v[88:91]
	v_mfma_f32_16x16x4_f32 v[92:95], v134, v145, v[92:95]
	v_mfma_f32_16x16x4_f32 v[112:115], v134, v146, v[112:115]
	v_mfma_f32_16x16x4_f32 v[116:119], v134, v147, v[116:119]
	global_load_dwordx4 v[144:147], v149, s[10:11]
	v_add_u32_e32 v149, 0x2000, v149
	ds_read_b32 v134, v148 offset:7424
	s_waitcnt vmcnt(2) lgkmcnt(2)
	v_mfma_f32_16x16x4_f32 v[88:91], v132, v136, v[88:91]
	v_mfma_f32_16x16x4_f32 v[92:95], v132, v137, v[92:95]
	v_mfma_f32_16x16x4_f32 v[112:115], v132, v138, v[112:115]
	v_mfma_f32_16x16x4_f32 v[116:119], v132, v139, v[116:119]
	global_load_dwordx4 v[136:139], v149, s[10:11]
	v_add_u32_e32 v149, 0x2000, v149
	ds_read_b32 v132, v148 offset:7680
	s_waitcnt vmcnt(2) lgkmcnt(2)
	v_mfma_f32_16x16x4_f32 v[88:91], v133, v140, v[88:91]
	v_mfma_f32_16x16x4_f32 v[92:95], v133, v141, v[92:95]
	v_mfma_f32_16x16x4_f32 v[112:115], v133, v142, v[112:115]
	v_mfma_f32_16x16x4_f32 v[116:119], v133, v143, v[116:119]
	global_load_dwordx4 v[140:143], v149, s[10:11]
	v_add_u32_e32 v149, 0x2000, v149
	ds_read_b32 v133, v148 offset:7936
	s_waitcnt vmcnt(2) lgkmcnt(2)
	v_mfma_f32_16x16x4_f32 v[88:91], v134, v144, v[88:91]
	v_mfma_f32_16x16x4_f32 v[92:95], v134, v145, v[92:95]
	v_mfma_f32_16x16x4_f32 v[112:115], v134, v146, v[112:115]
	v_mfma_f32_16x16x4_f32 v[116:119], v134, v147, v[116:119]
	s_waitcnt vmcnt(1) lgkmcnt(1)
	v_mfma_f32_16x16x4_f32 v[88:91], v132, v136, v[88:91]
	v_mfma_f32_16x16x4_f32 v[92:95], v132, v137, v[92:95]
	v_mfma_f32_16x16x4_f32 v[112:115], v132, v138, v[112:115]
	v_mfma_f32_16x16x4_f32 v[116:119], v132, v139, v[116:119]
	s_waitcnt vmcnt(0) lgkmcnt(0)
	v_mfma_f32_16x16x4_f32 v[88:91], v133, v140, v[88:91]
	v_mfma_f32_16x16x4_f32 v[92:95], v133, v141, v[92:95]
	v_mfma_f32_16x16x4_f32 v[112:115], v133, v142, v[112:115]
	v_mfma_f32_16x16x4_f32 v[116:119], v133, v143, v[116:119]
	s_nop 15
	s_nop 3
	s_mov_b32 s46, 0
	s_mov_b64 s[24:25], -1
	ds_write_b32 v150, v88 offset:0
	ds_write_b32 v150, v89 offset:2048
	ds_write_b32 v150, v90 offset:4096
	ds_write_b32 v150, v91 offset:6144
	ds_write_b32 v150, v92 offset:4
	ds_write_b32 v150, v93 offset:2052
	ds_write_b32 v150, v94 offset:4100
	ds_write_b32 v150, v95 offset:6148
	ds_write_b32 v150, v112 offset:8
	ds_write_b32 v150, v113 offset:2056
	ds_write_b32 v150, v114 offset:4104
	ds_write_b32 v150, v115 offset:6152
	ds_write_b32 v150, v116 offset:12
	ds_write_b32 v150, v117 offset:2060
	ds_write_b32 v150, v118 offset:4108
	ds_write_b32 v150, v119 offset:6156
	s_waitcnt lgkmcnt(0)
	s_barrier
